# sample attention: LDS reads of the q.k and P.V inner loops issued in batches with counted waits; prologue x-copy and final-norm loops issue all loads of a row before one wait
# speedup vs baseline: 1.0207x; 1.0207x over previous
; __device__ __forceinline__ u32x2 pk4(f32x4 v) { return (u32x2){pk2(v.x, v.y), pk2(v.z, v.w)}; }
; __device__ __forceinline__ float wave_sum(float x) { x = row_sum16(x); x += __shfl_xor(x, 16); x += __shfl_xor(x, 32); return __builtin_bit_cast(float, __builtin_amdgcn_readfirstlane(__builtin_bit_cast(int, x))); }
; __global__ void __launch_bounds__(512, 2) mega_fwd(Params p) {
;     ...
;         for (int row = gw; row < MT; row += NGW) {
;             const float* src = row < MP ? p.in[I_XP] + (size_t)row * 1024 : p.in[I_XS] + (size_t)(row - MP) * 1024;
;             float s = 0.f;
; #pragma unroll
;             for (int j = 0; j < 4; ++j) { const f32x4 v = *(const f32x4*)(src + j * 256 + lane * 4); s += (v.x * v.x + v.y * v.y) + (v.z * v.z + v.w * v.w);
;                 *(f32x4*)(X + (size_t)row * 1024 + j * 256 + lane * 4) = v; *(u32x2*)(XB + (size_t)row * 1024 + j * 256 + lane * 4) = pk4(v); }
;             s = wave_sum(s);
;             if (lane < 16) SSQ1[(size_t)row * 16 + lane] = lane == 0 ? s : 0.f;
;             if (lane == 0) ((float*)(ws + WS_RS1))[row] = __builtin_amdgcn_rsqf(s * (1.0f / 1024.0f) + 1e-6f);
.LBB0_104:
	global_load_dwordx4 v[10:13], v1, s[14:15]
	global_load_dwordx4 v[14:17], v1, s[14:15] offset:1024
	global_load_dwordx4 v[18:21], v1, s[14:15] offset:2048
	global_load_dwordx4 v[22:25], v1, s[14:15] offset:3072
	s_lshl_b64 s[20:21], s[12:13], 12
	s_lshl_b64 s[22:23], s[12:13], 11
	v_lshl_add_u64 v[26:27], v[2:3], 0, s[20:21]
	v_lshl_add_u64 v[28:29], v[4:5], 0, s[22:23]
	s_waitcnt vmcnt(0)
	flat_store_dwordx4 v[26:27], v[10:13]
	flat_store_dwordx4 v[26:27], v[14:17] offset:1024
	flat_store_dwordx4 v[26:27], v[18:21] offset:2048
	flat_store_dwordx4 v[26:27], v[22:25] offset:3072
	v_mul_f32_e32 v30, v10, v10
	v_fmac_f32_e32 v30, v11, v11
	v_fmac_f32_e32 v30, v12, v12
	v_fmac_f32_e32 v30, v13, v13
	v_fmac_f32_e32 v30, v14, v14
	v_fmac_f32_e32 v30, v15, v15
	v_fmac_f32_e32 v30, v16, v16
	v_fmac_f32_e32 v30, v17, v17
	v_fmac_f32_e32 v30, v18, v18
	v_fmac_f32_e32 v30, v19, v19
	v_fmac_f32_e32 v30, v20, v20
	v_fmac_f32_e32 v30, v21, v21
	v_fmac_f32_e32 v30, v22, v22
	v_fmac_f32_e32 v30, v23, v23
	v_fmac_f32_e32 v30, v24, v24
	v_fmac_f32_e32 v30, v25, v25
	v_cvt_pk_bf16_f32 v10, v10, v11
	v_cvt_pk_bf16_f32 v11, v12, v13
	v_cvt_pk_bf16_f32 v14, v14, v15
	v_cvt_pk_bf16_f32 v15, v16, v17
	v_cvt_pk_bf16_f32 v18, v18, v19
	v_cvt_pk_bf16_f32 v19, v20, v21
	v_cvt_pk_bf16_f32 v22, v22, v23
	v_cvt_pk_bf16_f32 v23, v24, v25
	flat_store_dwordx2 v[28:29], v[10:11]
	flat_store_dwordx2 v[28:29], v[14:15] offset:512
	flat_store_dwordx2 v[28:29], v[18:19] offset:1024
	flat_store_dwordx2 v[28:29], v[22:23] offset:1536
	s_nop 0
	v_mov_b32_e32 v10, v30
	v_mov_b32_e32 v30, 0
	v_mov_b32_e32 v11, 0
	s_nop 0
	v_add_f32_dpp v10, v10, v10 quad_perm:[1,0,3,2] row_mask:0xf bank_mask:0xf bound_ctrl:1
	s_nop 1
	v_add_f32_dpp v10, v10, v10 quad_perm:[2,3,0,1] row_mask:0xf bank_mask:0xf bound_ctrl:1
	s_nop 1
	v_add_f32_dpp v10, v10, v10 row_ror:4 row_mask:0xf bank_mask:0xf bound_ctrl:1
	s_nop 1
	v_add_f32_dpp v10, v10, v10 row_ror:8 row_mask:0xf bank_mask:0xf bound_ctrl:1
	s_nop 1
	v_mov_b32_dpp v30, v10 row_bcast:15 row_mask:0xa bank_mask:0xf
	v_add_f32_e32 v10, v10, v30
	s_nop 1
	v_mov_b32_dpp v11, v10 row_bcast:31 row_mask:0xc bank_mask:0xf
	v_add_f32_e32 v10, v10, v11
	s_nop 0
	v_readlane_b32 s4, v10, 63
	s_and_saveexec_b64 s[14:15], vcc
	s_cbranch_execz .LBB0_106
	s_lshl_b64 s[20:21], s[12:13], 6
	v_mov_b32_e32 v12, s4
	v_lshl_add_u64 v[10:11], v[6:7], 0, s[20:21]
	v_cndmask_b32_e64 v12, 0, v12, s[2:3]
	flat_store_dword v[10:11], v12

; __device__ __forceinline__ void fox_sample_unit(const Params& p, int l, int b, int h, float* sf) {
;     ...
;                 const int key = tid >> 2, tq = tid & 3;
;                 if (key < nk) {
;                     float acc[4] = {0.f, 0.f, 0.f, 0.f};
; #pragma unroll 4
;                     for (int d4 = 0; d4 < 16; ++d4) { const f32x4 kv = *(const f32x4*)(sT + key * 68 + d4 * 4);
; #pragma unroll
;                         for (int i = 0; i < 4; ++i) { const f32x4 qv = *(const f32x4*)(sQ + (tq * 4 + i) * 64 + d4 * 4); acc[i] += (kv.x * qv.x + kv.y * qv.y) + (kv.z * qv.z + kv.w * qv.w); } }
;                     const int gkey = tile * 128 + key; const float bias = -CKS[gkey] * LOG2E;
; #pragma unroll
;                     for (int i = 0; i < 4; ++i) { const int t = tq * 4 + i; float s = acc[i] + bias; if (gkey > 1024 + t) s = -INFINITY; sS[t * 1056 + gkey] = s; }
;                 }
;             } else {
;                 const int t = tid >> 5, d2 = (tid & 31) * 2;
;                 for (int key = 0; key < nk; ++key) { const float pv = sS[t * 1056 + tile * 128 + key]; const f32x2v v = *(const f32x2v*)(sT + key * 68 + d2); o0 = fmaf(pv, v.x, o0); o1 = fmaf(pv, v.y, o1); }
.LBB0_744:
	ds_read_b128 v[134:137], v103
	ds_read_b128 v[138:141], v103 offset:16
	ds_read_b128 v[142:145], v103 offset:32
	ds_read_b128 v[146:149], v103 offset:48
	v_add_u32_e32 v211, 0x11800, v102
	ds_read_b64 v[168:169], v211 offset:0
	ds_read_b64 v[170:171], v211 offset:272
	ds_read_b64 v[172:173], v211 offset:544
	ds_read_b64 v[174:175], v211 offset:816
	ds_read_b64 v[176:177], v211 offset:1088
	ds_read_b64 v[178:179], v211 offset:1360
	ds_read_b64 v[180:181], v211 offset:1632
	ds_read_b64 v[182:183], v211 offset:1904
	ds_read_b64 v[184:185], v211 offset:2176
	ds_read_b64 v[212:213], v211 offset:2448
	s_add_i32 s58, s58, -16
	v_add_u32_e32 v103, 64, v103
	v_add_u32_e32 v102, 0x1100, v102
	s_cmp_lg_u32 s58, 0
	s_waitcnt lgkmcnt(0)
	v_pk_fma_f32 v[100:101], v[134:135], v[168:169], v[100:101] op_sel_hi:[0,1,1]
	ds_read_b64 v[168:169], v211 offset:2720
	v_pk_fma_f32 v[100:101], v[134:135], v[170:171], v[100:101] op_sel:[1,0,0]
	ds_read_b64 v[170:171], v211 offset:2992
	v_pk_fma_f32 v[100:101], v[136:137], v[172:173], v[100:101] op_sel_hi:[0,1,1]
	ds_read_b64 v[172:173], v211 offset:3264
	v_pk_fma_f32 v[100:101], v[136:137], v[174:175], v[100:101] op_sel:[1,0,0]
	ds_read_b64 v[174:175], v211 offset:3536
	v_pk_fma_f32 v[100:101], v[138:139], v[176:177], v[100:101] op_sel_hi:[0,1,1]
	ds_read_b64 v[176:177], v211 offset:3808
	v_pk_fma_f32 v[100:101], v[138:139], v[178:179], v[100:101] op_sel:[1,0,0]
	ds_read_b64 v[178:179], v211 offset:4080
	v_pk_fma_f32 v[100:101], v[140:141], v[180:181], v[100:101] op_sel_hi:[0,1,1]
	v_pk_fma_f32 v[100:101], v[140:141], v[182:183], v[100:101] op_sel:[1,0,0]
	v_pk_fma_f32 v[100:101], v[142:143], v[184:185], v[100:101] op_sel_hi:[0,1,1]
	v_pk_fma_f32 v[100:101], v[142:143], v[212:213], v[100:101] op_sel:[1,0,0]
	s_waitcnt lgkmcnt(0)
	v_pk_fma_f32 v[100:101], v[144:145], v[168:169], v[100:101] op_sel_hi:[0,1,1]
	v_pk_fma_f32 v[100:101], v[144:145], v[170:171], v[100:101] op_sel:[1,0,0]
	v_pk_fma_f32 v[100:101], v[146:147], v[172:173], v[100:101] op_sel_hi:[0,1,1]
	v_pk_fma_f32 v[100:101], v[146:147], v[174:175], v[100:101] op_sel:[1,0,0]
	v_pk_fma_f32 v[100:101], v[148:149], v[176:177], v[100:101] op_sel_hi:[0,1,1]
	v_pk_fma_f32 v[100:101], v[148:149], v[178:179], v[100:101] op_sel:[1,0,0]
	s_cbranch_scc1 .LBB0_744
	s_mov_b64 s[82:83], 0
.LBB0_746:
	s_and_b64 vcc, exec, s[82:83]
	s_cbranch_vccz .LBB0_752
	s_and_saveexec_b64 vcc, s[20:21]
	s_cbranch_execz .LBB0_751
	v_mov_b32_e32 v100, 0
	s_mov_b32 s58, 0
	v_mov_b32_e32 v101, v100
	v_mov_b32_e32 v102, v100
	v_mov_b32_e32 v103, v100
	v_mov_b32_e32 v104, 0
	v_mov_b32_e32 v105, 0
	v_mov_b32_e32 v154, 0
	v_mov_b32_e32 v155, 0
	v_mov_b32_e32 v184, 0
	v_mov_b32_e32 v185, 0
	v_mov_b32_e32 v212, 0
	v_mov_b32_e32 v213, 0
.LBB0_749:
	v_add_u32_e32 v133, s58, v119
	v_add_u32_e32 v156, s58, v108
	v_add_u32_e32 v133, 0x11800, v133
	ds_read_b128 v[134:137], v133 offset:0
	ds_read_b128 v[138:141], v156 offset:0
	ds_read_b128 v[142:145], v156 offset:256
	ds_read_b128 v[146:149], v156 offset:512
	ds_read_b128 v[150:153], v156 offset:768
	ds_read_b128 v[158:161], v133 offset:16
	ds_read_b128 v[168:171], v156 offset:16
	ds_read_b128 v[172:175], v156 offset:272
	ds_read_b128 v[176:179], v156 offset:528
	ds_read_b128 v[180:183], v156 offset:784
	s_add_i32 s58, s58, 64
	s_cmpk_eq_i32 s58, 0x100
	s_waitcnt lgkmcnt(5)
	v_pk_fma_f32 v[104:105], v[134:135], v[138:139], v[104:105]
	v_pk_fma_f32 v[154:155], v[134:135], v[142:143], v[154:155]
	v_pk_fma_f32 v[184:185], v[134:135], v[146:147], v[184:185]
	v_pk_fma_f32 v[212:213], v[134:135], v[150:151], v[212:213]
	v_pk_fma_f32 v[104:105], v[136:137], v[140:141], v[104:105]
	v_pk_fma_f32 v[154:155], v[136:137], v[144:145], v[154:155]
	v_pk_fma_f32 v[184:185], v[136:137], v[148:149], v[184:185]
	v_pk_fma_f32 v[212:213], v[136:137], v[152:153], v[212:213]
	ds_read_b128 v[134:137], v133 offset:32
	ds_read_b128 v[138:141], v156 offset:32
	ds_read_b128 v[142:145], v156 offset:288
	ds_read_b128 v[146:149], v156 offset:544
	ds_read_b128 v[150:153], v156 offset:800
	s_waitcnt lgkmcnt(5)
	v_pk_fma_f32 v[104:105], v[158:159], v[168:169], v[104:105]
	v_pk_fma_f32 v[154:155], v[158:159], v[172:173], v[154:155]
	v_pk_fma_f32 v[184:185], v[158:159], v[176:177], v[184:185]
	v_pk_fma_f32 v[212:213], v[158:159], v[180:181], v[212:213]
	v_pk_fma_f32 v[104:105], v[160:161], v[170:171], v[104:105]
	v_pk_fma_f32 v[154:155], v[160:161], v[174:175], v[154:155]
	v_pk_fma_f32 v[184:185], v[160:161], v[178:179], v[184:185]
	v_pk_fma_f32 v[212:213], v[160:161], v[182:183], v[212:213]
	ds_read_b128 v[158:161], v133 offset:48
	ds_read_b128 v[168:171], v156 offset:48
	ds_read_b128 v[172:175], v156 offset:304
	ds_read_b128 v[176:179], v156 offset:560
	ds_read_b128 v[180:183], v156 offset:816
	s_waitcnt lgkmcnt(5)
	v_pk_fma_f32 v[104:105], v[134:135], v[138:139], v[104:105]
	v_pk_fma_f32 v[154:155], v[134:135], v[142:143], v[154:155]
	v_pk_fma_f32 v[184:185], v[134:135], v[146:147], v[184:185]
	v_pk_fma_f32 v[212:213], v[134:135], v[150:151], v[212:213]
	v_pk_fma_f32 v[104:105], v[136:137], v[140:141], v[104:105]
	v_pk_fma_f32 v[154:155], v[136:137], v[144:145], v[154:155]
	v_pk_fma_f32 v[184:185], v[136:137], v[148:149], v[184:185]
	v_pk_fma_f32 v[212:213], v[136:137], v[152:153], v[212:213]
	s_waitcnt lgkmcnt(0)
	v_pk_fma_f32 v[104:105], v[158:159], v[168:169], v[104:105]
	v_pk_fma_f32 v[154:155], v[158:159], v[172:173], v[154:155]
	v_pk_fma_f32 v[184:185], v[158:159], v[176:177], v[184:185]
	v_pk_fma_f32 v[212:213], v[158:159], v[180:181], v[212:213]
	v_pk_fma_f32 v[104:105], v[160:161], v[170:171], v[104:105]
	v_pk_fma_f32 v[154:155], v[160:161], v[174:175], v[154:155]
	v_pk_fma_f32 v[184:185], v[160:161], v[178:179], v[184:185]
	v_pk_fma_f32 v[212:213], v[160:161], v[182:183], v[212:213]
	s_cbranch_scc0 .LBB0_749
	s_nop 0
	v_add_f32_e32 v100, v104, v105
	v_add_f32_e32 v101, v154, v155
	v_add_f32_e32 v102, v184, v185
	v_add_f32_e32 v103, v212, v213
	global_load_dword v104, v[46:47], off
	s_waitcnt vmcnt(0)
	v_fmamk_f32 v100, v104, 0xbfb8aa3b, v100
	v_fmac_f32_e32 v101, 0xbfb8aa3b, v104
	v_fmamk_f32 v102, v104, 0xbfb8aa3b, v102
	v_fmac_f32_e32 v103, 0xbfb8aa3b, v104
	ds_write_b32 v115, v100 offset:4096
	ds_write_b32 v115, v101 offset:8320
	ds_write_b32 v115, v102 offset:12544
	ds_write_b32 v115, v103 offset:16768

; __device__ __forceinline__ void fox_sample_unit(const Params& p, int l, int b, int h, float* sf) {
;     ...
;                 const int key = tid >> 2, tq = tid & 3;
;                 if (key < nk) {
;                     float acc[4] = {0.f, 0.f, 0.f, 0.f};
; #pragma unroll 4
;                     for (int d4 = 0; d4 < 16; ++d4) { const f32x4 kv = *(const f32x4*)(sT + key * 68 + d4 * 4);
; #pragma unroll
;                         for (int i = 0; i < 4; ++i) { const f32x4 qv = *(const f32x4*)(sQ + (tq * 4 + i) * 64 + d4 * 4); acc[i] += (kv.x * qv.x + kv.y * qv.y) + (kv.z * qv.z + kv.w * qv.w); } }
;                     const int gkey = tile * 128 + key; const float bias = -CKS[gkey] * LOG2E;
; #pragma unroll
;                     for (int i = 0; i < 4; ++i) { const int t = tq * 4 + i; float s = acc[i] + bias; if (gkey > 1024 + t) s = -INFINITY; sS[t * 1056 + gkey] = s; }
;                 }
;             } else {
;                 const int t = tid >> 5, d2 = (tid & 31) * 2;
;                 for (int key = 0; key < nk; ++key) { const float pv = sS[t * 1056 + tile * 128 + key]; const f32x2v v = *(const f32x2v*)(sT + key * 68 + d2); o0 = fmaf(pv, v.x, o0); o1 = fmaf(pv, v.y, o1); }
.LBB0_759:
	ds_read_b128 v[134:137], v105
	ds_read_b128 v[138:141], v105 offset:16
	ds_read_b128 v[142:145], v105 offset:32
	ds_read_b128 v[146:149], v105 offset:48
	v_add_u32_e32 v211, 0x11800, v104
	ds_read_b64 v[168:169], v211 offset:0
	ds_read_b64 v[170:171], v211 offset:272
	ds_read_b64 v[172:173], v211 offset:544
	ds_read_b64 v[174:175], v211 offset:816
	ds_read_b64 v[176:177], v211 offset:1088
	ds_read_b64 v[178:179], v211 offset:1360
	ds_read_b64 v[180:181], v211 offset:1632
	ds_read_b64 v[182:183], v211 offset:1904
	ds_read_b64 v[184:185], v211 offset:2176
	ds_read_b64 v[212:213], v211 offset:2448
	s_add_i32 s58, s58, -16
	v_add_u32_e32 v105, 64, v105
	v_add_u32_e32 v104, 0x1100, v104
	s_cmp_eq_u32 s58, 0
	s_waitcnt lgkmcnt(0)
	v_pk_fma_f32 v[102:103], v[134:135], v[168:169], v[102:103] op_sel_hi:[0,1,1]
	ds_read_b64 v[168:169], v211 offset:2720
	v_pk_fma_f32 v[102:103], v[134:135], v[170:171], v[102:103] op_sel:[1,0,0]
	ds_read_b64 v[170:171], v211 offset:2992
	v_pk_fma_f32 v[102:103], v[136:137], v[172:173], v[102:103] op_sel_hi:[0,1,1]
	ds_read_b64 v[172:173], v211 offset:3264
	v_pk_fma_f32 v[102:103], v[136:137], v[174:175], v[102:103] op_sel:[1,0,0]
	ds_read_b64 v[174:175], v211 offset:3536
	v_pk_fma_f32 v[102:103], v[138:139], v[176:177], v[102:103] op_sel_hi:[0,1,1]
	ds_read_b64 v[176:177], v211 offset:3808
	v_pk_fma_f32 v[102:103], v[138:139], v[178:179], v[102:103] op_sel:[1,0,0]
	ds_read_b64 v[178:179], v211 offset:4080
	v_pk_fma_f32 v[102:103], v[140:141], v[180:181], v[102:103] op_sel_hi:[0,1,1]
	v_pk_fma_f32 v[102:103], v[140:141], v[182:183], v[102:103] op_sel:[1,0,0]
	v_pk_fma_f32 v[102:103], v[142:143], v[184:185], v[102:103] op_sel_hi:[0,1,1]
	v_pk_fma_f32 v[102:103], v[142:143], v[212:213], v[102:103] op_sel:[1,0,0]
	s_waitcnt lgkmcnt(0)
	v_pk_fma_f32 v[102:103], v[144:145], v[168:169], v[102:103] op_sel_hi:[0,1,1]
	v_pk_fma_f32 v[102:103], v[144:145], v[170:171], v[102:103] op_sel:[1,0,0]
	v_pk_fma_f32 v[102:103], v[146:147], v[172:173], v[102:103] op_sel_hi:[0,1,1]
	v_pk_fma_f32 v[102:103], v[146:147], v[174:175], v[102:103] op_sel:[1,0,0]
	v_pk_fma_f32 v[102:103], v[148:149], v[176:177], v[102:103] op_sel_hi:[0,1,1]
	v_pk_fma_f32 v[102:103], v[148:149], v[178:179], v[102:103] op_sel:[1,0,0]
	s_cbranch_scc0 .LBB0_759
	s_mov_b64 s[82:83], 0
.LBB0_761:
	s_and_b64 vcc, exec, s[82:83]
	s_cbranch_vccz .LBB0_767
	s_and_saveexec_b64 vcc, s[20:21]
	s_cbranch_execz .LBB0_766
	v_mov_b32_e32 v102, 0
	s_mov_b32 s58, 0
	v_mov_b32_e32 v103, v102
	v_mov_b32_e32 v104, v102
	v_mov_b32_e32 v105, v102
	v_mov_b32_e32 v178, 0
	v_mov_b32_e32 v179, 0
	v_mov_b32_e32 v180, 0
	v_mov_b32_e32 v181, 0
	v_mov_b32_e32 v182, 0
	v_mov_b32_e32 v183, 0
	v_mov_b32_e32 v184, 0
	v_mov_b32_e32 v185, 0
.LBB0_764:
	v_add_u32_e32 v133, s58, v119
	v_add_u32_e32 v211, s58, v108
	v_add_u32_e32 v133, 0x11800, v133
	ds_read_b128 v[134:137], v133 offset:0
	ds_read_b128 v[138:141], v211 offset:0
	ds_read_b128 v[142:145], v211 offset:256
	ds_read_b128 v[146:149], v211 offset:512
	ds_read_b128 v[150:153], v211 offset:768
	ds_read_b128 v[154:157], v133 offset:16
	ds_read_b128 v[158:161], v211 offset:16
	ds_read_b128 v[166:169], v211 offset:272
	ds_read_b128 v[170:173], v211 offset:528
	ds_read_b128 v[174:177], v211 offset:784
	s_add_i32 s58, s58, 64
	s_cmpk_lg_i32 s58, 0x100
	s_waitcnt lgkmcnt(5)
	v_pk_fma_f32 v[178:179], v[134:135], v[138:139], v[178:179]
	v_pk_fma_f32 v[180:181], v[134:135], v[142:143], v[180:181]
	v_pk_fma_f32 v[182:183], v[134:135], v[146:147], v[182:183]
	v_pk_fma_f32 v[184:185], v[134:135], v[150:151], v[184:185]
	v_pk_fma_f32 v[178:179], v[136:137], v[140:141], v[178:179]
	v_pk_fma_f32 v[180:181], v[136:137], v[144:145], v[180:181]
	v_pk_fma_f32 v[182:183], v[136:137], v[148:149], v[182:183]
	v_pk_fma_f32 v[184:185], v[136:137], v[152:153], v[184:185]
	ds_read_b128 v[134:137], v133 offset:32
	ds_read_b128 v[138:141], v211 offset:32
	ds_read_b128 v[142:145], v211 offset:288
	ds_read_b128 v[146:149], v211 offset:544
	ds_read_b128 v[150:153], v211 offset:800
	s_waitcnt lgkmcnt(5)
	v_pk_fma_f32 v[178:179], v[154:155], v[158:159], v[178:179]
	v_pk_fma_f32 v[180:181], v[154:155], v[166:167], v[180:181]
	v_pk_fma_f32 v[182:183], v[154:155], v[170:171], v[182:183]
	v_pk_fma_f32 v[184:185], v[154:155], v[174:175], v[184:185]
	v_pk_fma_f32 v[178:179], v[156:157], v[160:161], v[178:179]
	v_pk_fma_f32 v[180:181], v[156:157], v[168:169], v[180:181]
	v_pk_fma_f32 v[182:183], v[156:157], v[172:173], v[182:183]
	v_pk_fma_f32 v[184:185], v[156:157], v[176:177], v[184:185]
	ds_read_b128 v[154:157], v133 offset:48
	ds_read_b128 v[158:161], v211 offset:48
	ds_read_b128 v[166:169], v211 offset:304
	ds_read_b128 v[170:173], v211 offset:560
	ds_read_b128 v[174:177], v211 offset:816
	s_waitcnt lgkmcnt(5)
	v_pk_fma_f32 v[178:179], v[134:135], v[138:139], v[178:179]
	v_pk_fma_f32 v[180:181], v[134:135], v[142:143], v[180:181]
	v_pk_fma_f32 v[182:183], v[134:135], v[146:147], v[182:183]
	v_pk_fma_f32 v[184:185], v[134:135], v[150:151], v[184:185]
	v_pk_fma_f32 v[178:179], v[136:137], v[140:141], v[178:179]
	v_pk_fma_f32 v[180:181], v[136:137], v[144:145], v[180:181]
	v_pk_fma_f32 v[182:183], v[136:137], v[148:149], v[182:183]
	v_pk_fma_f32 v[184:185], v[136:137], v[152:153], v[184:185]
	s_waitcnt lgkmcnt(0)
	v_pk_fma_f32 v[178:179], v[154:155], v[158:159], v[178:179]
	v_pk_fma_f32 v[180:181], v[154:155], v[166:167], v[180:181]
	v_pk_fma_f32 v[182:183], v[154:155], v[170:171], v[182:183]
	v_pk_fma_f32 v[184:185], v[154:155], v[174:175], v[184:185]
	v_pk_fma_f32 v[178:179], v[156:157], v[160:161], v[178:179]
	v_pk_fma_f32 v[180:181], v[156:157], v[168:169], v[180:181]
	v_pk_fma_f32 v[182:183], v[156:157], v[172:173], v[182:183]
	v_pk_fma_f32 v[184:185], v[156:157], v[176:177], v[184:185]
	s_cbranch_scc1 .LBB0_764
	s_nop 0
	v_add_f32_e32 v102, v178, v179
	v_add_f32_e32 v103, v180, v181
	v_add_f32_e32 v104, v182, v183
	v_add_f32_e32 v105, v184, v185
	global_load_dword v133, v[46:47], off offset:512
	s_waitcnt vmcnt(0)
	v_fmamk_f32 v102, v133, 0xbfb8aa3b, v102
	v_fmac_f32_e32 v103, 0xbfb8aa3b, v133
	v_fmamk_f32 v104, v133, 0xbfb8aa3b, v104
	v_fmac_f32_e32 v105, 0xbfb8aa3b, v133
	ds_write_b32 v115, v102 offset:4608
	ds_write_b32 v115, v103 offset:8832
	ds_write_b32 v115, v104 offset:13056
	ds_write_b32 v115, v105 offset:17280

; __device__ __forceinline__ void fox_sample_unit(const Params& p, int l, int b, int h, float* sf) {
;     ...
;                 const int key = tid >> 2, tq = tid & 3;
;                 if (key < nk) {
;                     float acc[4] = {0.f, 0.f, 0.f, 0.f};
; #pragma unroll 4
;                     for (int d4 = 0; d4 < 16; ++d4) { const f32x4 kv = *(const f32x4*)(sT + key * 68 + d4 * 4);
; #pragma unroll
;                         for (int i = 0; i < 4; ++i) { const f32x4 qv = *(const f32x4*)(sQ + (tq * 4 + i) * 64 + d4 * 4); acc[i] += (kv.x * qv.x + kv.y * qv.y) + (kv.z * qv.z + kv.w * qv.w); } }
;                     const int gkey = tile * 128 + key; const float bias = -CKS[gkey] * LOG2E;
; #pragma unroll
;                     for (int i = 0; i < 4; ++i) { const int t = tq * 4 + i; float s = acc[i] + bias; if (gkey > 1024 + t) s = -INFINITY; sS[t * 1056 + gkey] = s; }
;                 }
;             } else {
;                 const int t = tid >> 5, d2 = (tid & 31) * 2;
;                 for (int key = 0; key < nk; ++key) { const float pv = sS[t * 1056 + tile * 128 + key]; const f32x2v v = *(const f32x2v*)(sT + key * 68 + d2); o0 = fmaf(pv, v.x, o0); o1 = fmaf(pv, v.y, o1); }
.LBB0_774:
	ds_read_b128 v[134:137], v101
	ds_read_b128 v[138:141], v101 offset:16
	ds_read_b128 v[142:145], v101 offset:32
	ds_read_b128 v[146:149], v101 offset:48
	v_add_u32_e32 v211, 0x11800, v100
	ds_read_b64 v[168:169], v211 offset:0
	ds_read_b64 v[170:171], v211 offset:272
	ds_read_b64 v[172:173], v211 offset:544
	ds_read_b64 v[174:175], v211 offset:816
	ds_read_b64 v[176:177], v211 offset:1088
	ds_read_b64 v[178:179], v211 offset:1360
	ds_read_b64 v[180:181], v211 offset:1632
	ds_read_b64 v[182:183], v211 offset:1904
	ds_read_b64 v[184:185], v211 offset:2176
	ds_read_b64 v[212:213], v211 offset:2448
	s_add_i32 s58, s58, -16
	v_add_u32_e32 v101, 64, v101
	v_add_u32_e32 v100, 0x1100, v100
	s_cmp_eq_u32 s58, 0
	s_waitcnt lgkmcnt(0)
	v_pk_fma_f32 v[104:105], v[134:135], v[168:169], v[104:105] op_sel_hi:[0,1,1]
	ds_read_b64 v[168:169], v211 offset:2720
	v_pk_fma_f32 v[104:105], v[134:135], v[170:171], v[104:105] op_sel:[1,0,0]
	ds_read_b64 v[170:171], v211 offset:2992
	v_pk_fma_f32 v[104:105], v[136:137], v[172:173], v[104:105] op_sel_hi:[0,1,1]
	ds_read_b64 v[172:173], v211 offset:3264
	v_pk_fma_f32 v[104:105], v[136:137], v[174:175], v[104:105] op_sel:[1,0,0]
	ds_read_b64 v[174:175], v211 offset:3536
	v_pk_fma_f32 v[104:105], v[138:139], v[176:177], v[104:105] op_sel_hi:[0,1,1]
	ds_read_b64 v[176:177], v211 offset:3808
	v_pk_fma_f32 v[104:105], v[138:139], v[178:179], v[104:105] op_sel:[1,0,0]
	ds_read_b64 v[178:179], v211 offset:4080
	v_pk_fma_f32 v[104:105], v[140:141], v[180:181], v[104:105] op_sel_hi:[0,1,1]
	v_pk_fma_f32 v[104:105], v[140:141], v[182:183], v[104:105] op_sel:[1,0,0]
	v_pk_fma_f32 v[104:105], v[142:143], v[184:185], v[104:105] op_sel_hi:[0,1,1]
	v_pk_fma_f32 v[104:105], v[142:143], v[212:213], v[104:105] op_sel:[1,0,0]
	s_waitcnt lgkmcnt(0)
	v_pk_fma_f32 v[104:105], v[144:145], v[168:169], v[104:105] op_sel_hi:[0,1,1]
	v_pk_fma_f32 v[104:105], v[144:145], v[170:171], v[104:105] op_sel:[1,0,0]
	v_pk_fma_f32 v[104:105], v[146:147], v[172:173], v[104:105] op_sel_hi:[0,1,1]
	v_pk_fma_f32 v[104:105], v[146:147], v[174:175], v[104:105] op_sel:[1,0,0]
	v_pk_fma_f32 v[104:105], v[148:149], v[176:177], v[104:105] op_sel_hi:[0,1,1]
	v_pk_fma_f32 v[104:105], v[148:149], v[178:179], v[104:105] op_sel:[1,0,0]
	s_cbranch_scc0 .LBB0_774
	s_mov_b64 s[82:83], 0
.LBB0_776:
	s_and_b64 vcc, exec, s[82:83]
	s_cbranch_vccz .LBB0_782
	s_and_saveexec_b64 vcc, s[20:21]
	s_cbranch_execz .LBB0_781
	v_mov_b32_e32 v100, 0
	s_mov_b32 s58, 0
	v_mov_b32_e32 v101, v100
	v_mov_b32_e32 v104, v100
	v_mov_b32_e32 v105, v100
	v_mov_b32_e32 v178, 0
	v_mov_b32_e32 v179, 0
	v_mov_b32_e32 v180, 0
	v_mov_b32_e32 v181, 0
	v_mov_b32_e32 v182, 0
	v_mov_b32_e32 v183, 0
	v_mov_b32_e32 v184, 0
	v_mov_b32_e32 v185, 0
.LBB0_779:
	v_add_u32_e32 v133, s58, v119
	v_add_u32_e32 v211, s58, v108
	v_add_u32_e32 v133, 0x11800, v133
	ds_read_b128 v[134:137], v133 offset:0
	ds_read_b128 v[138:141], v211 offset:0
	ds_read_b128 v[142:145], v211 offset:256
	ds_read_b128 v[146:149], v211 offset:512
	ds_read_b128 v[150:153], v211 offset:768
	ds_read_b128 v[154:157], v133 offset:16
	ds_read_b128 v[158:161], v211 offset:16
	ds_read_b128 v[166:169], v211 offset:272
	ds_read_b128 v[170:173], v211 offset:528
	ds_read_b128 v[174:177], v211 offset:784
	s_add_i32 s58, s58, 64
	s_cmpk_lg_i32 s58, 0x100
	s_waitcnt lgkmcnt(5)
	v_pk_fma_f32 v[178:179], v[134:135], v[138:139], v[178:179]
	v_pk_fma_f32 v[180:181], v[134:135], v[142:143], v[180:181]
	v_pk_fma_f32 v[182:183], v[134:135], v[146:147], v[182:183]
	v_pk_fma_f32 v[184:185], v[134:135], v[150:151], v[184:185]
	v_pk_fma_f32 v[178:179], v[136:137], v[140:141], v[178:179]
	v_pk_fma_f32 v[180:181], v[136:137], v[144:145], v[180:181]
	v_pk_fma_f32 v[182:183], v[136:137], v[148:149], v[182:183]
	v_pk_fma_f32 v[184:185], v[136:137], v[152:153], v[184:185]
	ds_read_b128 v[134:137], v133 offset:32
	ds_read_b128 v[138:141], v211 offset:32
	ds_read_b128 v[142:145], v211 offset:288
	ds_read_b128 v[146:149], v211 offset:544
	ds_read_b128 v[150:153], v211 offset:800
	s_waitcnt lgkmcnt(5)
	v_pk_fma_f32 v[178:179], v[154:155], v[158:159], v[178:179]
	v_pk_fma_f32 v[180:181], v[154:155], v[166:167], v[180:181]
	v_pk_fma_f32 v[182:183], v[154:155], v[170:171], v[182:183]
	v_pk_fma_f32 v[184:185], v[154:155], v[174:175], v[184:185]
	v_pk_fma_f32 v[178:179], v[156:157], v[160:161], v[178:179]
	v_pk_fma_f32 v[180:181], v[156:157], v[168:169], v[180:181]
	v_pk_fma_f32 v[182:183], v[156:157], v[172:173], v[182:183]
	v_pk_fma_f32 v[184:185], v[156:157], v[176:177], v[184:185]
	ds_read_b128 v[154:157], v133 offset:48
	ds_read_b128 v[158:161], v211 offset:48
	ds_read_b128 v[166:169], v211 offset:304
	ds_read_b128 v[170:173], v211 offset:560
	ds_read_b128 v[174:177], v211 offset:816
	s_waitcnt lgkmcnt(5)
	v_pk_fma_f32 v[178:179], v[134:135], v[138:139], v[178:179]
	v_pk_fma_f32 v[180:181], v[134:135], v[142:143], v[180:181]
	v_pk_fma_f32 v[182:183], v[134:135], v[146:147], v[182:183]
	v_pk_fma_f32 v[184:185], v[134:135], v[150:151], v[184:185]
	v_pk_fma_f32 v[178:179], v[136:137], v[140:141], v[178:179]
	v_pk_fma_f32 v[180:181], v[136:137], v[144:145], v[180:181]
	v_pk_fma_f32 v[182:183], v[136:137], v[148:149], v[182:183]
	v_pk_fma_f32 v[184:185], v[136:137], v[152:153], v[184:185]
	s_waitcnt lgkmcnt(0)
	v_pk_fma_f32 v[178:179], v[154:155], v[158:159], v[178:179]
	v_pk_fma_f32 v[180:181], v[154:155], v[166:167], v[180:181]
	v_pk_fma_f32 v[182:183], v[154:155], v[170:171], v[182:183]
	v_pk_fma_f32 v[184:185], v[154:155], v[174:175], v[184:185]
	v_pk_fma_f32 v[178:179], v[156:157], v[160:161], v[178:179]
	v_pk_fma_f32 v[180:181], v[156:157], v[168:169], v[180:181]
	v_pk_fma_f32 v[182:183], v[156:157], v[172:173], v[182:183]
	v_pk_fma_f32 v[184:185], v[156:157], v[176:177], v[184:185]
	s_cbranch_scc1 .LBB0_779
	s_nop 0
	v_add_f32_e32 v100, v178, v179
	v_add_f32_e32 v101, v180, v181
	v_add_f32_e32 v104, v182, v183
	v_add_f32_e32 v105, v184, v185
	global_load_dword v133, v[46:47], off offset:1024
	s_waitcnt vmcnt(0)
	v_fmamk_f32 v100, v133, 0xbfb8aa3b, v100
	v_fmac_f32_e32 v101, 0xbfb8aa3b, v133
	v_fmamk_f32 v104, v133, 0xbfb8aa3b, v104
	v_fmac_f32_e32 v105, 0xbfb8aa3b, v133
	ds_write_b32 v115, v100 offset:5120
	ds_write_b32 v115, v101 offset:9344
	ds_write_b32 v115, v104 offset:13568
	ds_write_b32 v115, v105 offset:17792

; __device__ __forceinline__ void fox_sample_unit(const Params& p, int l, int b, int h, float* sf) {
;     ...
;                 const int key = tid >> 2, tq = tid & 3;
;                 if (key < nk) {
;                     float acc[4] = {0.f, 0.f, 0.f, 0.f};
; #pragma unroll 4
;                     for (int d4 = 0; d4 < 16; ++d4) { const f32x4 kv = *(const f32x4*)(sT + key * 68 + d4 * 4);
; #pragma unroll
;                         for (int i = 0; i < 4; ++i) { const f32x4 qv = *(const f32x4*)(sQ + (tq * 4 + i) * 64 + d4 * 4); acc[i] += (kv.x * qv.x + kv.y * qv.y) + (kv.z * qv.z + kv.w * qv.w); } }
;                     const int gkey = tile * 128 + key; const float bias = -CKS[gkey] * LOG2E;
; #pragma unroll
;                     for (int i = 0; i < 4; ++i) { const int t = tq * 4 + i; float s = acc[i] + bias; if (gkey > 1024 + t) s = -INFINITY; sS[t * 1056 + gkey] = s; }
;                 }
;             } else {
;                 const int t = tid >> 5, d2 = (tid & 31) * 2;
;                 for (int key = 0; key < nk; ++key) { const float pv = sS[t * 1056 + tile * 128 + key]; const f32x2v v = *(const f32x2v*)(sT + key * 68 + d2); o0 = fmaf(pv, v.x, o0); o1 = fmaf(pv, v.y, o1); }
.LBB0_789:
	ds_read_b128 v[134:137], v103
	ds_read_b128 v[138:141], v103 offset:16
	ds_read_b128 v[142:145], v103 offset:32
	ds_read_b128 v[146:149], v103 offset:48
	v_add_u32_e32 v211, 0x11800, v102
	ds_read_b64 v[168:169], v211 offset:0
	ds_read_b64 v[170:171], v211 offset:272
	ds_read_b64 v[172:173], v211 offset:544
	ds_read_b64 v[174:175], v211 offset:816
	ds_read_b64 v[176:177], v211 offset:1088
	ds_read_b64 v[178:179], v211 offset:1360
	ds_read_b64 v[180:181], v211 offset:1632
	ds_read_b64 v[182:183], v211 offset:1904
	ds_read_b64 v[184:185], v211 offset:2176
	ds_read_b64 v[212:213], v211 offset:2448
	s_add_i32 s58, s58, -16
	v_add_u32_e32 v103, 64, v103
	v_add_u32_e32 v102, 0x1100, v102
	s_cmp_eq_u32 s58, 0
	s_waitcnt lgkmcnt(0)
	v_pk_fma_f32 v[100:101], v[134:135], v[168:169], v[100:101] op_sel_hi:[0,1,1]
	ds_read_b64 v[168:169], v211 offset:2720
	v_pk_fma_f32 v[100:101], v[134:135], v[170:171], v[100:101] op_sel:[1,0,0]
	ds_read_b64 v[170:171], v211 offset:2992
	v_pk_fma_f32 v[100:101], v[136:137], v[172:173], v[100:101] op_sel_hi:[0,1,1]
	ds_read_b64 v[172:173], v211 offset:3264
	v_pk_fma_f32 v[100:101], v[136:137], v[174:175], v[100:101] op_sel:[1,0,0]
	ds_read_b64 v[174:175], v211 offset:3536
	v_pk_fma_f32 v[100:101], v[138:139], v[176:177], v[100:101] op_sel_hi:[0,1,1]
	ds_read_b64 v[176:177], v211 offset:3808
	v_pk_fma_f32 v[100:101], v[138:139], v[178:179], v[100:101] op_sel:[1,0,0]
	ds_read_b64 v[178:179], v211 offset:4080
	v_pk_fma_f32 v[100:101], v[140:141], v[180:181], v[100:101] op_sel_hi:[0,1,1]
	v_pk_fma_f32 v[100:101], v[140:141], v[182:183], v[100:101] op_sel:[1,0,0]
	v_pk_fma_f32 v[100:101], v[142:143], v[184:185], v[100:101] op_sel_hi:[0,1,1]
	v_pk_fma_f32 v[100:101], v[142:143], v[212:213], v[100:101] op_sel:[1,0,0]
	s_waitcnt lgkmcnt(0)
	v_pk_fma_f32 v[100:101], v[144:145], v[168:169], v[100:101] op_sel_hi:[0,1,1]
	v_pk_fma_f32 v[100:101], v[144:145], v[170:171], v[100:101] op_sel:[1,0,0]
	v_pk_fma_f32 v[100:101], v[146:147], v[172:173], v[100:101] op_sel_hi:[0,1,1]
	v_pk_fma_f32 v[100:101], v[146:147], v[174:175], v[100:101] op_sel:[1,0,0]
	v_pk_fma_f32 v[100:101], v[148:149], v[176:177], v[100:101] op_sel_hi:[0,1,1]
	v_pk_fma_f32 v[100:101], v[148:149], v[178:179], v[100:101] op_sel:[1,0,0]
	s_cbranch_scc0 .LBB0_789
	s_mov_b64 s[82:83], 0
.LBB0_791:
	s_and_b64 vcc, exec, s[82:83]
	s_cbranch_vccz .LBB0_797
	s_and_saveexec_b64 vcc, s[20:21]
	s_cbranch_execz .LBB0_796
	v_mov_b32_e32 v100, 0
	s_mov_b32 s58, 0
	v_mov_b32_e32 v101, v100
	v_mov_b32_e32 v102, v100
	v_mov_b32_e32 v103, v100
	v_mov_b32_e32 v178, 0
	v_mov_b32_e32 v179, 0
	v_mov_b32_e32 v180, 0
	v_mov_b32_e32 v181, 0
	v_mov_b32_e32 v182, 0
	v_mov_b32_e32 v183, 0
	v_mov_b32_e32 v184, 0
	v_mov_b32_e32 v185, 0
.LBB0_794:
	v_add_u32_e32 v133, s58, v119
	v_add_u32_e32 v211, s58, v108
	v_add_u32_e32 v133, 0x11800, v133
	ds_read_b128 v[134:137], v133 offset:0
	ds_read_b128 v[138:141], v211 offset:0
	ds_read_b128 v[142:145], v211 offset:256
	ds_read_b128 v[146:149], v211 offset:512
	ds_read_b128 v[150:153], v211 offset:768
	ds_read_b128 v[154:157], v133 offset:16
	ds_read_b128 v[158:161], v211 offset:16
	ds_read_b128 v[166:169], v211 offset:272
	ds_read_b128 v[170:173], v211 offset:528
	ds_read_b128 v[174:177], v211 offset:784
	s_add_i32 s58, s58, 64
	s_cmpk_lg_i32 s58, 0x100
	s_waitcnt lgkmcnt(5)
	v_pk_fma_f32 v[178:179], v[134:135], v[138:139], v[178:179]
	v_pk_fma_f32 v[180:181], v[134:135], v[142:143], v[180:181]
	v_pk_fma_f32 v[182:183], v[134:135], v[146:147], v[182:183]
	v_pk_fma_f32 v[184:185], v[134:135], v[150:151], v[184:185]
	v_pk_fma_f32 v[178:179], v[136:137], v[140:141], v[178:179]
	v_pk_fma_f32 v[180:181], v[136:137], v[144:145], v[180:181]
	v_pk_fma_f32 v[182:183], v[136:137], v[148:149], v[182:183]
	v_pk_fma_f32 v[184:185], v[136:137], v[152:153], v[184:185]
	ds_read_b128 v[134:137], v133 offset:32
	ds_read_b128 v[138:141], v211 offset:32
	ds_read_b128 v[142:145], v211 offset:288
	ds_read_b128 v[146:149], v211 offset:544
	ds_read_b128 v[150:153], v211 offset:800
	s_waitcnt lgkmcnt(5)
	v_pk_fma_f32 v[178:179], v[154:155], v[158:159], v[178:179]
	v_pk_fma_f32 v[180:181], v[154:155], v[166:167], v[180:181]
	v_pk_fma_f32 v[182:183], v[154:155], v[170:171], v[182:183]
	v_pk_fma_f32 v[184:185], v[154:155], v[174:175], v[184:185]
	v_pk_fma_f32 v[178:179], v[156:157], v[160:161], v[178:179]
	v_pk_fma_f32 v[180:181], v[156:157], v[168:169], v[180:181]
	v_pk_fma_f32 v[182:183], v[156:157], v[172:173], v[182:183]
	v_pk_fma_f32 v[184:185], v[156:157], v[176:177], v[184:185]
	ds_read_b128 v[154:157], v133 offset:48
	ds_read_b128 v[158:161], v211 offset:48
	ds_read_b128 v[166:169], v211 offset:304
	ds_read_b128 v[170:173], v211 offset:560
	ds_read_b128 v[174:177], v211 offset:816
	s_waitcnt lgkmcnt(5)
	v_pk_fma_f32 v[178:179], v[134:135], v[138:139], v[178:179]
	v_pk_fma_f32 v[180:181], v[134:135], v[142:143], v[180:181]
	v_pk_fma_f32 v[182:183], v[134:135], v[146:147], v[182:183]
	v_pk_fma_f32 v[184:185], v[134:135], v[150:151], v[184:185]
	v_pk_fma_f32 v[178:179], v[136:137], v[140:141], v[178:179]
	v_pk_fma_f32 v[180:181], v[136:137], v[144:145], v[180:181]
	v_pk_fma_f32 v[182:183], v[136:137], v[148:149], v[182:183]
	v_pk_fma_f32 v[184:185], v[136:137], v[152:153], v[184:185]
	s_waitcnt lgkmcnt(0)
	v_pk_fma_f32 v[178:179], v[154:155], v[158:159], v[178:179]
	v_pk_fma_f32 v[180:181], v[154:155], v[166:167], v[180:181]
	v_pk_fma_f32 v[182:183], v[154:155], v[170:171], v[182:183]
	v_pk_fma_f32 v[184:185], v[154:155], v[174:175], v[184:185]
	v_pk_fma_f32 v[178:179], v[156:157], v[160:161], v[178:179]
	v_pk_fma_f32 v[180:181], v[156:157], v[168:169], v[180:181]
	v_pk_fma_f32 v[182:183], v[156:157], v[172:173], v[182:183]
	v_pk_fma_f32 v[184:185], v[156:157], v[176:177], v[184:185]
	s_cbranch_scc1 .LBB0_794
	s_nop 0
	v_add_f32_e32 v100, v178, v179
	v_add_f32_e32 v101, v180, v181
	v_add_f32_e32 v102, v182, v183
	v_add_f32_e32 v103, v184, v185
	global_load_dword v133, v[46:47], off offset:1536
	s_waitcnt vmcnt(0)
	v_fmamk_f32 v100, v133, 0xbfb8aa3b, v100
	v_fmac_f32_e32 v101, 0xbfb8aa3b, v133
	v_fmamk_f32 v102, v133, 0xbfb8aa3b, v102
	v_fmac_f32_e32 v103, 0xbfb8aa3b, v133
	ds_write_b32 v115, v100 offset:5632
	ds_write_b32 v115, v101 offset:9856
	ds_write_b32 v115, v102 offset:14080
	ds_write_b32 v115, v103 offset:18304

; __device__ __forceinline__ void fox_sample_unit(const Params& p, int l, int b, int h, float* sf) {
;     ...
;                 const int key = tid >> 2, tq = tid & 3;
;                 if (key < nk) {
;                     float acc[4] = {0.f, 0.f, 0.f, 0.f};
; #pragma unroll 4
;                     for (int d4 = 0; d4 < 16; ++d4) { const f32x4 kv = *(const f32x4*)(sT + key * 68 + d4 * 4);
; #pragma unroll
;                         for (int i = 0; i < 4; ++i) { const f32x4 qv = *(const f32x4*)(sQ + (tq * 4 + i) * 64 + d4 * 4); acc[i] += (kv.x * qv.x + kv.y * qv.y) + (kv.z * qv.z + kv.w * qv.w); } }
;                     const int gkey = tile * 128 + key; const float bias = -CKS[gkey] * LOG2E;
; #pragma unroll
;                     for (int i = 0; i < 4; ++i) { const int t = tq * 4 + i; float s = acc[i] + bias; if (gkey > 1024 + t) s = -INFINITY; sS[t * 1056 + gkey] = s; }
.LBB0_809:
	v_add_u32_e32 v133, s58, v119
	v_add_u32_e32 v211, s58, v108
	v_add_u32_e32 v133, 0x11800, v133
	ds_read_b128 v[134:137], v133 offset:0
	ds_read_b128 v[138:141], v211 offset:0
	ds_read_b128 v[142:145], v211 offset:256
	ds_read_b128 v[146:149], v211 offset:512
	ds_read_b128 v[150:153], v211 offset:768
	ds_read_b128 v[154:157], v133 offset:16
	ds_read_b128 v[158:161], v211 offset:16
	ds_read_b128 v[166:169], v211 offset:272
	ds_read_b128 v[170:173], v211 offset:528
	ds_read_b128 v[174:177], v211 offset:784
	s_add_i32 s58, s58, 64
	s_cmpk_lg_i32 s58, 0x100
	s_waitcnt lgkmcnt(5)
	v_pk_fma_f32 v[178:179], v[134:135], v[138:139], v[178:179]
	v_pk_fma_f32 v[180:181], v[134:135], v[142:143], v[180:181]
	v_pk_fma_f32 v[182:183], v[134:135], v[146:147], v[182:183]
	v_pk_fma_f32 v[184:185], v[134:135], v[150:151], v[184:185]
	v_pk_fma_f32 v[178:179], v[136:137], v[140:141], v[178:179]
	v_pk_fma_f32 v[180:181], v[136:137], v[144:145], v[180:181]
	v_pk_fma_f32 v[182:183], v[136:137], v[148:149], v[182:183]
	v_pk_fma_f32 v[184:185], v[136:137], v[152:153], v[184:185]
	ds_read_b128 v[134:137], v133 offset:32
	ds_read_b128 v[138:141], v211 offset:32
	ds_read_b128 v[142:145], v211 offset:288
	ds_read_b128 v[146:149], v211 offset:544
	ds_read_b128 v[150:153], v211 offset:800
	s_waitcnt lgkmcnt(5)
	v_pk_fma_f32 v[178:179], v[154:155], v[158:159], v[178:179]
	v_pk_fma_f32 v[180:181], v[154:155], v[166:167], v[180:181]
	v_pk_fma_f32 v[182:183], v[154:155], v[170:171], v[182:183]
	v_pk_fma_f32 v[184:185], v[154:155], v[174:175], v[184:185]
	v_pk_fma_f32 v[178:179], v[156:157], v[160:161], v[178:179]
	v_pk_fma_f32 v[180:181], v[156:157], v[168:169], v[180:181]
	v_pk_fma_f32 v[182:183], v[156:157], v[172:173], v[182:183]
	v_pk_fma_f32 v[184:185], v[156:157], v[176:177], v[184:185]
	ds_read_b128 v[154:157], v133 offset:48
	ds_read_b128 v[158:161], v211 offset:48
	ds_read_b128 v[166:169], v211 offset:304
	ds_read_b128 v[170:173], v211 offset:560
	ds_read_b128 v[174:177], v211 offset:816
	s_waitcnt lgkmcnt(5)
	v_pk_fma_f32 v[178:179], v[134:135], v[138:139], v[178:179]
	v_pk_fma_f32 v[180:181], v[134:135], v[142:143], v[180:181]
	v_pk_fma_f32 v[182:183], v[134:135], v[146:147], v[182:183]
	v_pk_fma_f32 v[184:185], v[134:135], v[150:151], v[184:185]
	v_pk_fma_f32 v[178:179], v[136:137], v[140:141], v[178:179]
	v_pk_fma_f32 v[180:181], v[136:137], v[144:145], v[180:181]
	v_pk_fma_f32 v[182:183], v[136:137], v[148:149], v[182:183]
	v_pk_fma_f32 v[184:185], v[136:137], v[152:153], v[184:185]
	s_waitcnt lgkmcnt(0)
	v_pk_fma_f32 v[178:179], v[154:155], v[158:159], v[178:179]
	v_pk_fma_f32 v[180:181], v[154:155], v[166:167], v[180:181]
	v_pk_fma_f32 v[182:183], v[154:155], v[170:171], v[182:183]
	v_pk_fma_f32 v[184:185], v[154:155], v[174:175], v[184:185]
	v_pk_fma_f32 v[178:179], v[156:157], v[160:161], v[178:179]
	v_pk_fma_f32 v[180:181], v[156:157], v[168:169], v[180:181]
	v_pk_fma_f32 v[182:183], v[156:157], v[172:173], v[182:183]
	v_pk_fma_f32 v[184:185], v[156:157], v[176:177], v[184:185]
	s_cbranch_scc1 .LBB0_809
	s_nop 0
	v_add_f32_e32 v102, v178, v179
	v_add_f32_e32 v103, v180, v181
	v_add_f32_e32 v104, v182, v183
	v_add_f32_e32 v105, v184, v185
	global_load_dword v133, v[46:47], off offset:2048
	s_waitcnt vmcnt(0)
	v_fmamk_f32 v102, v133, 0xbfb8aa3b, v102
	v_fmac_f32_e32 v103, 0xbfb8aa3b, v133
	v_fmamk_f32 v104, v133, 0xbfb8aa3b, v104
	v_fmac_f32_e32 v105, 0xbfb8aa3b, v133
	ds_write_b32 v115, v102 offset:6144
	ds_write_b32 v115, v103 offset:10368
	ds_write_b32 v115, v104 offset:14592
	ds_write_b32 v115, v105 offset:18816

; __device__ __forceinline__ void fox_sample_unit(const Params& p, int l, int b, int h, float* sf) {
;     ...
;                 const int t = tid >> 5, d2 = (tid & 31) * 2;
;                 for (int key = 0; key < nk; ++key) { const float pv = sS[t * 1056 + tile * 128 + key]; const f32x2v v = *(const f32x2v*)(sT + key * 68 + d2); o0 = fmaf(pv, v.x, o0); o1 = fmaf(pv, v.y, o1); }
.LBB0_819:
	ds_read_b128 v[134:137], v105
	ds_read_b128 v[138:141], v105 offset:16
	ds_read_b128 v[142:145], v105 offset:32
	ds_read_b128 v[146:149], v105 offset:48
	v_add_u32_e32 v211, 0x11800, v104
	ds_read_b64 v[168:169], v211 offset:0
	ds_read_b64 v[170:171], v211 offset:272
	ds_read_b64 v[172:173], v211 offset:544
	ds_read_b64 v[174:175], v211 offset:816
	ds_read_b64 v[176:177], v211 offset:1088
	ds_read_b64 v[178:179], v211 offset:1360
	ds_read_b64 v[180:181], v211 offset:1632
	ds_read_b64 v[182:183], v211 offset:1904
	ds_read_b64 v[184:185], v211 offset:2176
	ds_read_b64 v[212:213], v211 offset:2448
	s_add_i32 s58, s58, -16
	v_add_u32_e32 v105, 64, v105
	v_add_u32_e32 v104, 0x1100, v104
	s_cmp_eq_u32 s58, 0
	s_waitcnt lgkmcnt(0)
	v_pk_fma_f32 v[100:101], v[134:135], v[168:169], v[100:101] op_sel_hi:[0,1,1]
	ds_read_b64 v[168:169], v211 offset:2720
	v_pk_fma_f32 v[100:101], v[134:135], v[170:171], v[100:101] op_sel:[1,0,0]
	ds_read_b64 v[170:171], v211 offset:2992
	v_pk_fma_f32 v[100:101], v[136:137], v[172:173], v[100:101] op_sel_hi:[0,1,1]
	ds_read_b64 v[172:173], v211 offset:3264
	v_pk_fma_f32 v[100:101], v[136:137], v[174:175], v[100:101] op_sel:[1,0,0]
	ds_read_b64 v[174:175], v211 offset:3536
	v_pk_fma_f32 v[100:101], v[138:139], v[176:177], v[100:101] op_sel_hi:[0,1,1]
	ds_read_b64 v[176:177], v211 offset:3808
	v_pk_fma_f32 v[100:101], v[138:139], v[178:179], v[100:101] op_sel:[1,0,0]
	ds_read_b64 v[178:179], v211 offset:4080
	v_pk_fma_f32 v[100:101], v[140:141], v[180:181], v[100:101] op_sel_hi:[0,1,1]
	v_pk_fma_f32 v[100:101], v[140:141], v[182:183], v[100:101] op_sel:[1,0,0]
	v_pk_fma_f32 v[100:101], v[142:143], v[184:185], v[100:101] op_sel_hi:[0,1,1]
	v_pk_fma_f32 v[100:101], v[142:143], v[212:213], v[100:101] op_sel:[1,0,0]
	s_waitcnt lgkmcnt(0)
	v_pk_fma_f32 v[100:101], v[144:145], v[168:169], v[100:101] op_sel_hi:[0,1,1]
	v_pk_fma_f32 v[100:101], v[144:145], v[170:171], v[100:101] op_sel:[1,0,0]
	v_pk_fma_f32 v[100:101], v[146:147], v[172:173], v[100:101] op_sel_hi:[0,1,1]
	v_pk_fma_f32 v[100:101], v[146:147], v[174:175], v[100:101] op_sel:[1,0,0]
	v_pk_fma_f32 v[100:101], v[148:149], v[176:177], v[100:101] op_sel_hi:[0,1,1]
	v_pk_fma_f32 v[100:101], v[148:149], v[178:179], v[100:101] op_sel:[1,0,0]
	s_cbranch_scc0 .LBB0_819
	s_mov_b64 s[82:83], 0

; __device__ __forceinline__ void fox_sample_unit(const Params& p, int l, int b, int h, float* sf) {
;     ...
;                 const int key = tid >> 2, tq = tid & 3;
;                 if (key < nk) {
;                     float acc[4] = {0.f, 0.f, 0.f, 0.f};
; #pragma unroll 4
;                     for (int d4 = 0; d4 < 16; ++d4) { const f32x4 kv = *(const f32x4*)(sT + key * 68 + d4 * 4);
; #pragma unroll
;                         for (int i = 0; i < 4; ++i) { const f32x4 qv = *(const f32x4*)(sQ + (tq * 4 + i) * 64 + d4 * 4); acc[i] += (kv.x * qv.x + kv.y * qv.y) + (kv.z * qv.z + kv.w * qv.w); } }
;                     const int gkey = tile * 128 + key; const float bias = -CKS[gkey] * LOG2E;
; #pragma unroll
;                     for (int i = 0; i < 4; ++i) { const int t = tq * 4 + i; float s = acc[i] + bias; if (gkey > 1024 + t) s = -INFINITY; sS[t * 1056 + gkey] = s; }
.LBB0_824:
	v_add_u32_e32 v133, s58, v119
	v_add_u32_e32 v211, s58, v108
	v_add_u32_e32 v133, 0x11800, v133
	ds_read_b128 v[134:137], v133 offset:0
	ds_read_b128 v[138:141], v211 offset:0
	ds_read_b128 v[142:145], v211 offset:256
	ds_read_b128 v[146:149], v211 offset:512
	ds_read_b128 v[150:153], v211 offset:768
	ds_read_b128 v[154:157], v133 offset:16
	ds_read_b128 v[158:161], v211 offset:16
	ds_read_b128 v[166:169], v211 offset:272
	ds_read_b128 v[170:173], v211 offset:528
	ds_read_b128 v[174:177], v211 offset:784
	s_add_i32 s58, s58, 64
	s_cmpk_lg_i32 s58, 0x100
	s_waitcnt lgkmcnt(5)
	v_pk_fma_f32 v[178:179], v[134:135], v[138:139], v[178:179]
	v_pk_fma_f32 v[180:181], v[134:135], v[142:143], v[180:181]
	v_pk_fma_f32 v[182:183], v[134:135], v[146:147], v[182:183]
	v_pk_fma_f32 v[184:185], v[134:135], v[150:151], v[184:185]
	v_pk_fma_f32 v[178:179], v[136:137], v[140:141], v[178:179]
	v_pk_fma_f32 v[180:181], v[136:137], v[144:145], v[180:181]
	v_pk_fma_f32 v[182:183], v[136:137], v[148:149], v[182:183]
	v_pk_fma_f32 v[184:185], v[136:137], v[152:153], v[184:185]
	ds_read_b128 v[134:137], v133 offset:32
	ds_read_b128 v[138:141], v211 offset:32
	ds_read_b128 v[142:145], v211 offset:288
	ds_read_b128 v[146:149], v211 offset:544
	ds_read_b128 v[150:153], v211 offset:800
	s_waitcnt lgkmcnt(5)
	v_pk_fma_f32 v[178:179], v[154:155], v[158:159], v[178:179]
	v_pk_fma_f32 v[180:181], v[154:155], v[166:167], v[180:181]
	v_pk_fma_f32 v[182:183], v[154:155], v[170:171], v[182:183]
	v_pk_fma_f32 v[184:185], v[154:155], v[174:175], v[184:185]
	v_pk_fma_f32 v[178:179], v[156:157], v[160:161], v[178:179]
	v_pk_fma_f32 v[180:181], v[156:157], v[168:169], v[180:181]
	v_pk_fma_f32 v[182:183], v[156:157], v[172:173], v[182:183]
	v_pk_fma_f32 v[184:185], v[156:157], v[176:177], v[184:185]
	ds_read_b128 v[154:157], v133 offset:48
	ds_read_b128 v[158:161], v211 offset:48
	ds_read_b128 v[166:169], v211 offset:304
	ds_read_b128 v[170:173], v211 offset:560
	ds_read_b128 v[174:177], v211 offset:816
	s_waitcnt lgkmcnt(5)
	v_pk_fma_f32 v[178:179], v[134:135], v[138:139], v[178:179]
	v_pk_fma_f32 v[180:181], v[134:135], v[142:143], v[180:181]
	v_pk_fma_f32 v[182:183], v[134:135], v[146:147], v[182:183]
	v_pk_fma_f32 v[184:185], v[134:135], v[150:151], v[184:185]
	v_pk_fma_f32 v[178:179], v[136:137], v[140:141], v[178:179]
	v_pk_fma_f32 v[180:181], v[136:137], v[144:145], v[180:181]
	v_pk_fma_f32 v[182:183], v[136:137], v[148:149], v[182:183]
	v_pk_fma_f32 v[184:185], v[136:137], v[152:153], v[184:185]
	s_waitcnt lgkmcnt(0)
	v_pk_fma_f32 v[178:179], v[154:155], v[158:159], v[178:179]
	v_pk_fma_f32 v[180:181], v[154:155], v[166:167], v[180:181]
	v_pk_fma_f32 v[182:183], v[154:155], v[170:171], v[182:183]
	v_pk_fma_f32 v[184:185], v[154:155], v[174:175], v[184:185]
	v_pk_fma_f32 v[178:179], v[156:157], v[160:161], v[178:179]
	v_pk_fma_f32 v[180:181], v[156:157], v[168:169], v[180:181]
	v_pk_fma_f32 v[182:183], v[156:157], v[172:173], v[182:183]
	v_pk_fma_f32 v[184:185], v[156:157], v[176:177], v[184:185]
	s_cbranch_scc1 .LBB0_824
	s_nop 0
	v_add_f32_e32 v100, v178, v179
	v_add_f32_e32 v101, v180, v181
	v_add_f32_e32 v104, v182, v183
	v_add_f32_e32 v105, v184, v185
	global_load_dword v133, v[46:47], off offset:2560
	s_waitcnt vmcnt(0)
	v_fmamk_f32 v100, v133, 0xbfb8aa3b, v100
	v_fmac_f32_e32 v101, 0xbfb8aa3b, v133
	v_fmamk_f32 v104, v133, 0xbfb8aa3b, v104
	v_fmac_f32_e32 v105, 0xbfb8aa3b, v133
	ds_write_b32 v115, v100 offset:6656
	ds_write_b32 v115, v101 offset:10880
	ds_write_b32 v115, v104 offset:15104
	ds_write_b32 v115, v105 offset:19328

; __device__ __forceinline__ void fox_sample_unit(const Params& p, int l, int b, int h, float* sf) {
;     ...
;                 const int key = tid >> 2, tq = tid & 3;
;                 if (key < nk) {
;                     float acc[4] = {0.f, 0.f, 0.f, 0.f};
; #pragma unroll 4
;                     for (int d4 = 0; d4 < 16; ++d4) { const f32x4 kv = *(const f32x4*)(sT + key * 68 + d4 * 4);
; #pragma unroll
;                         for (int i = 0; i < 4; ++i) { const f32x4 qv = *(const f32x4*)(sQ + (tq * 4 + i) * 64 + d4 * 4); acc[i] += (kv.x * qv.x + kv.y * qv.y) + (kv.z * qv.z + kv.w * qv.w); } }
;                     const int gkey = tile * 128 + key; const float bias = -CKS[gkey] * LOG2E;
; #pragma unroll
;                     for (int i = 0; i < 4; ++i) { const int t = tq * 4 + i; float s = acc[i] + bias; if (gkey > 1024 + t) s = -INFINITY; sS[t * 1056 + gkey] = s; }
;                 }
;             } else {
;                 const int t = tid >> 5, d2 = (tid & 31) * 2;
;                 for (int key = 0; key < nk; ++key) { const float pv = sS[t * 1056 + tile * 128 + key]; const f32x2v v = *(const f32x2v*)(sT + key * 68 + d2); o0 = fmaf(pv, v.x, o0); o1 = fmaf(pv, v.y, o1); }
.LBB0_834:
	ds_read_b128 v[134:137], v103
	ds_read_b128 v[138:141], v103 offset:16
	ds_read_b128 v[142:145], v103 offset:32
	ds_read_b128 v[146:149], v103 offset:48
	v_add_u32_e32 v211, 0x11800, v102
	ds_read_b64 v[168:169], v211 offset:0
	ds_read_b64 v[170:171], v211 offset:272
	ds_read_b64 v[172:173], v211 offset:544
	ds_read_b64 v[174:175], v211 offset:816
	ds_read_b64 v[176:177], v211 offset:1088
	ds_read_b64 v[178:179], v211 offset:1360
	ds_read_b64 v[180:181], v211 offset:1632
	ds_read_b64 v[182:183], v211 offset:1904
	ds_read_b64 v[184:185], v211 offset:2176
	ds_read_b64 v[212:213], v211 offset:2448
	s_add_i32 s58, s58, -16
	v_add_u32_e32 v103, 64, v103
	v_add_u32_e32 v102, 0x1100, v102
	s_cmp_eq_u32 s58, 0
	s_waitcnt lgkmcnt(0)
	v_pk_fma_f32 v[98:99], v[134:135], v[168:169], v[98:99] op_sel_hi:[0,1,1]
	ds_read_b64 v[168:169], v211 offset:2720
	v_pk_fma_f32 v[98:99], v[134:135], v[170:171], v[98:99] op_sel:[1,0,0]
	ds_read_b64 v[170:171], v211 offset:2992
	v_pk_fma_f32 v[98:99], v[136:137], v[172:173], v[98:99] op_sel_hi:[0,1,1]
	ds_read_b64 v[172:173], v211 offset:3264
	v_pk_fma_f32 v[98:99], v[136:137], v[174:175], v[98:99] op_sel:[1,0,0]
	ds_read_b64 v[174:175], v211 offset:3536
	v_pk_fma_f32 v[98:99], v[138:139], v[176:177], v[98:99] op_sel_hi:[0,1,1]
	ds_read_b64 v[176:177], v211 offset:3808
	v_pk_fma_f32 v[98:99], v[138:139], v[178:179], v[98:99] op_sel:[1,0,0]
	ds_read_b64 v[178:179], v211 offset:4080
	v_pk_fma_f32 v[98:99], v[140:141], v[180:181], v[98:99] op_sel_hi:[0,1,1]
	v_pk_fma_f32 v[98:99], v[140:141], v[182:183], v[98:99] op_sel:[1,0,0]
	v_pk_fma_f32 v[98:99], v[142:143], v[184:185], v[98:99] op_sel_hi:[0,1,1]
	v_pk_fma_f32 v[98:99], v[142:143], v[212:213], v[98:99] op_sel:[1,0,0]
	s_waitcnt lgkmcnt(0)
	v_pk_fma_f32 v[98:99], v[144:145], v[168:169], v[98:99] op_sel_hi:[0,1,1]
	v_pk_fma_f32 v[98:99], v[144:145], v[170:171], v[98:99] op_sel:[1,0,0]
	v_pk_fma_f32 v[98:99], v[146:147], v[172:173], v[98:99] op_sel_hi:[0,1,1]
	v_pk_fma_f32 v[98:99], v[146:147], v[174:175], v[98:99] op_sel:[1,0,0]
	v_pk_fma_f32 v[98:99], v[148:149], v[176:177], v[98:99] op_sel_hi:[0,1,1]
	v_pk_fma_f32 v[98:99], v[148:149], v[178:179], v[98:99] op_sel:[1,0,0]
	s_cbranch_scc0 .LBB0_834
	s_mov_b64 s[82:83], 0
.LBB0_836:
	s_and_b64 vcc, exec, s[82:83]
	s_cbranch_vccz .LBB0_842
	s_and_saveexec_b64 vcc, s[20:21]
	s_cbranch_execz .LBB0_841
	v_mov_b32_e32 v98, 0
	s_mov_b32 s58, 0
	v_mov_b32_e32 v99, v98
	v_mov_b32_e32 v102, v98
	v_mov_b32_e32 v103, v98
	v_mov_b32_e32 v104, 0
	v_mov_b32_e32 v105, 0
	v_mov_b32_e32 v154, 0
	v_mov_b32_e32 v155, 0
	v_mov_b32_e32 v184, 0
	v_mov_b32_e32 v185, 0
	v_mov_b32_e32 v212, 0
	v_mov_b32_e32 v213, 0
.LBB0_839:
	v_add_u32_e32 v133, s58, v119
	v_add_u32_e32 v156, s58, v108
	v_add_u32_e32 v133, 0x11800, v133
	ds_read_b128 v[134:137], v133 offset:0
	ds_read_b128 v[138:141], v156 offset:0
	ds_read_b128 v[142:145], v156 offset:256
	ds_read_b128 v[146:149], v156 offset:512
	ds_read_b128 v[150:153], v156 offset:768
	ds_read_b128 v[158:161], v133 offset:16
	ds_read_b128 v[168:171], v156 offset:16
	ds_read_b128 v[172:175], v156 offset:272
	ds_read_b128 v[176:179], v156 offset:528
	ds_read_b128 v[180:183], v156 offset:784
	s_add_i32 s58, s58, 64
	s_cmpk_lg_i32 s58, 0x100
	s_waitcnt lgkmcnt(5)
	v_pk_fma_f32 v[104:105], v[134:135], v[138:139], v[104:105]
	v_pk_fma_f32 v[154:155], v[134:135], v[142:143], v[154:155]
	v_pk_fma_f32 v[184:185], v[134:135], v[146:147], v[184:185]
	v_pk_fma_f32 v[212:213], v[134:135], v[150:151], v[212:213]
	v_pk_fma_f32 v[104:105], v[136:137], v[140:141], v[104:105]
	v_pk_fma_f32 v[154:155], v[136:137], v[144:145], v[154:155]
	v_pk_fma_f32 v[184:185], v[136:137], v[148:149], v[184:185]
	v_pk_fma_f32 v[212:213], v[136:137], v[152:153], v[212:213]
	ds_read_b128 v[134:137], v133 offset:32
	ds_read_b128 v[138:141], v156 offset:32
	ds_read_b128 v[142:145], v156 offset:288
	ds_read_b128 v[146:149], v156 offset:544
	ds_read_b128 v[150:153], v156 offset:800
	s_waitcnt lgkmcnt(5)
	v_pk_fma_f32 v[104:105], v[158:159], v[168:169], v[104:105]
	v_pk_fma_f32 v[154:155], v[158:159], v[172:173], v[154:155]
	v_pk_fma_f32 v[184:185], v[158:159], v[176:177], v[184:185]
	v_pk_fma_f32 v[212:213], v[158:159], v[180:181], v[212:213]
	v_pk_fma_f32 v[104:105], v[160:161], v[170:171], v[104:105]
	v_pk_fma_f32 v[154:155], v[160:161], v[174:175], v[154:155]
	v_pk_fma_f32 v[184:185], v[160:161], v[178:179], v[184:185]
	v_pk_fma_f32 v[212:213], v[160:161], v[182:183], v[212:213]
	ds_read_b128 v[158:161], v133 offset:48
	ds_read_b128 v[168:171], v156 offset:48
	ds_read_b128 v[172:175], v156 offset:304
	ds_read_b128 v[176:179], v156 offset:560
	ds_read_b128 v[180:183], v156 offset:816
	s_waitcnt lgkmcnt(5)
	v_pk_fma_f32 v[104:105], v[134:135], v[138:139], v[104:105]
	v_pk_fma_f32 v[154:155], v[134:135], v[142:143], v[154:155]
	v_pk_fma_f32 v[184:185], v[134:135], v[146:147], v[184:185]
	v_pk_fma_f32 v[212:213], v[134:135], v[150:151], v[212:213]
	v_pk_fma_f32 v[104:105], v[136:137], v[140:141], v[104:105]
	v_pk_fma_f32 v[154:155], v[136:137], v[144:145], v[154:155]
	v_pk_fma_f32 v[184:185], v[136:137], v[148:149], v[184:185]
	v_pk_fma_f32 v[212:213], v[136:137], v[152:153], v[212:213]
	s_waitcnt lgkmcnt(0)
	v_pk_fma_f32 v[104:105], v[158:159], v[168:169], v[104:105]
	v_pk_fma_f32 v[154:155], v[158:159], v[172:173], v[154:155]
	v_pk_fma_f32 v[184:185], v[158:159], v[176:177], v[184:185]
	v_pk_fma_f32 v[212:213], v[158:159], v[180:181], v[212:213]
	v_pk_fma_f32 v[104:105], v[160:161], v[170:171], v[104:105]
	v_pk_fma_f32 v[154:155], v[160:161], v[174:175], v[154:155]
	v_pk_fma_f32 v[184:185], v[160:161], v[178:179], v[184:185]
	v_pk_fma_f32 v[212:213], v[160:161], v[182:183], v[212:213]
	s_cbranch_scc1 .LBB0_839
	s_nop 0
	v_add_f32_e32 v98, v104, v105
	v_add_f32_e32 v99, v154, v155
	v_add_f32_e32 v102, v184, v185
	v_add_f32_e32 v103, v212, v213
	global_load_dword v104, v[46:47], off offset:3072
	s_waitcnt vmcnt(0)
	v_fmamk_f32 v98, v104, 0xbfb8aa3b, v98
	v_fmac_f32_e32 v99, 0xbfb8aa3b, v104
	v_fmamk_f32 v102, v104, 0xbfb8aa3b, v102
	v_fmac_f32_e32 v103, 0xbfb8aa3b, v104
	ds_write_b32 v115, v98 offset:7168
	ds_write_b32 v115, v99 offset:11392
	ds_write_b32 v115, v102 offset:15616
	ds_write_b32 v115, v103 offset:19840

; __device__ __forceinline__ void fox_sample_unit(const Params& p, int l, int b, int h, float* sf) {
;     ...
;                 const int key = tid >> 2, tq = tid & 3;
;                 if (key < nk) {
;                     float acc[4] = {0.f, 0.f, 0.f, 0.f};
; #pragma unroll 4
;                     for (int d4 = 0; d4 < 16; ++d4) { const f32x4 kv = *(const f32x4*)(sT + key * 68 + d4 * 4);
; #pragma unroll
;                         for (int i = 0; i < 4; ++i) { const f32x4 qv = *(const f32x4*)(sQ + (tq * 4 + i) * 64 + d4 * 4); acc[i] += (kv.x * qv.x + kv.y * qv.y) + (kv.z * qv.z + kv.w * qv.w); } }
;                     const int gkey = tile * 128 + key; const float bias = -CKS[gkey] * LOG2E;
; #pragma unroll
;                     for (int i = 0; i < 4; ++i) { const int t = tq * 4 + i; float s = acc[i] + bias; if (gkey > 1024 + t) s = -INFINITY; sS[t * 1056 + gkey] = s; }
;                 }
;             } else {
;                 const int t = tid >> 5, d2 = (tid & 31) * 2;
;                 for (int key = 0; key < nk; ++key) { const float pv = sS[t * 1056 + tile * 128 + key]; const f32x2v v = *(const f32x2v*)(sT + key * 68 + d2); o0 = fmaf(pv, v.x, o0); o1 = fmaf(pv, v.y, o1); }
.LBB0_854:
	ds_read_b128 v[134:137], v103
	ds_read_b128 v[138:141], v103 offset:16
	ds_read_b128 v[142:145], v103 offset:32
	ds_read_b128 v[146:149], v103 offset:48
	v_add_u32_e32 v211, 0x11800, v102
	ds_read_b64 v[168:169], v211 offset:0
	ds_read_b64 v[170:171], v211 offset:272
	ds_read_b64 v[172:173], v211 offset:544
	ds_read_b64 v[174:175], v211 offset:816
	ds_read_b64 v[176:177], v211 offset:1088
	ds_read_b64 v[178:179], v211 offset:1360
	ds_read_b64 v[180:181], v211 offset:1632
	ds_read_b64 v[182:183], v211 offset:1904
	ds_read_b64 v[184:185], v211 offset:2176
	ds_read_b64 v[212:213], v211 offset:2448
	s_add_i32 s58, s58, -16
	v_add_u32_e32 v103, 64, v103
	v_add_u32_e32 v102, 0x1100, v102
	s_cmp_eq_u32 s58, 0
	s_waitcnt lgkmcnt(0)
	v_pk_fma_f32 v[100:101], v[134:135], v[168:169], v[100:101] op_sel_hi:[0,1,1]
	ds_read_b64 v[168:169], v211 offset:2720
	v_pk_fma_f32 v[100:101], v[134:135], v[170:171], v[100:101] op_sel:[1,0,0]
	ds_read_b64 v[170:171], v211 offset:2992
	v_pk_fma_f32 v[100:101], v[136:137], v[172:173], v[100:101] op_sel_hi:[0,1,1]
	ds_read_b64 v[172:173], v211 offset:3264
	v_pk_fma_f32 v[100:101], v[136:137], v[174:175], v[100:101] op_sel:[1,0,0]
	ds_read_b64 v[174:175], v211 offset:3536
	v_pk_fma_f32 v[100:101], v[138:139], v[176:177], v[100:101] op_sel_hi:[0,1,1]
	ds_read_b64 v[176:177], v211 offset:3808
	v_pk_fma_f32 v[100:101], v[138:139], v[178:179], v[100:101] op_sel:[1,0,0]
	ds_read_b64 v[178:179], v211 offset:4080
	v_pk_fma_f32 v[100:101], v[140:141], v[180:181], v[100:101] op_sel_hi:[0,1,1]
	v_pk_fma_f32 v[100:101], v[140:141], v[182:183], v[100:101] op_sel:[1,0,0]
	v_pk_fma_f32 v[100:101], v[142:143], v[184:185], v[100:101] op_sel_hi:[0,1,1]
	v_pk_fma_f32 v[100:101], v[142:143], v[212:213], v[100:101] op_sel:[1,0,0]
	s_waitcnt lgkmcnt(0)
	v_pk_fma_f32 v[100:101], v[144:145], v[168:169], v[100:101] op_sel_hi:[0,1,1]
	v_pk_fma_f32 v[100:101], v[144:145], v[170:171], v[100:101] op_sel:[1,0,0]
	v_pk_fma_f32 v[100:101], v[146:147], v[172:173], v[100:101] op_sel_hi:[0,1,1]
	v_pk_fma_f32 v[100:101], v[146:147], v[174:175], v[100:101] op_sel:[1,0,0]
	v_pk_fma_f32 v[100:101], v[148:149], v[176:177], v[100:101] op_sel_hi:[0,1,1]
	v_pk_fma_f32 v[100:101], v[148:149], v[178:179], v[100:101] op_sel:[1,0,0]
	s_cbranch_scc0 .LBB0_854
	s_mov_b64 s[68:69], 0
.LBB0_856:
	s_and_b64 vcc, exec, s[68:69]
	s_cbranch_vccz .LBB0_862
	s_and_saveexec_b64 s[68:69], s[20:21]
	s_cbranch_execz .LBB0_861
	v_mov_b32_e32 v100, 0
	s_mov_b32 s58, 0
	v_mov_b32_e32 v101, v100
	v_mov_b32_e32 v102, v100
	v_mov_b32_e32 v103, v100
	v_mov_b32_e32 v104, 0
	v_mov_b32_e32 v105, 0
	v_mov_b32_e32 v154, 0
	v_mov_b32_e32 v155, 0
	v_mov_b32_e32 v184, 0
	v_mov_b32_e32 v185, 0
	v_mov_b32_e32 v212, 0
	v_mov_b32_e32 v213, 0
.LBB0_859:
	v_add_u32_e32 v133, s58, v119
	v_add_u32_e32 v156, s58, v108
	v_add_u32_e32 v133, 0x11800, v133
	ds_read_b128 v[134:137], v133 offset:0
	ds_read_b128 v[138:141], v156 offset:0
	ds_read_b128 v[142:145], v156 offset:256
	ds_read_b128 v[146:149], v156 offset:512
	ds_read_b128 v[150:153], v156 offset:768
	ds_read_b128 v[158:161], v133 offset:16
	ds_read_b128 v[168:171], v156 offset:16
	ds_read_b128 v[172:175], v156 offset:272
	ds_read_b128 v[176:179], v156 offset:528
	ds_read_b128 v[180:183], v156 offset:784
	s_add_i32 s58, s58, 64
	s_cmpk_lg_i32 s58, 0x100
	s_waitcnt lgkmcnt(5)
	v_pk_fma_f32 v[104:105], v[134:135], v[138:139], v[104:105]
	v_pk_fma_f32 v[154:155], v[134:135], v[142:143], v[154:155]
	v_pk_fma_f32 v[184:185], v[134:135], v[146:147], v[184:185]
	v_pk_fma_f32 v[212:213], v[134:135], v[150:151], v[212:213]
	v_pk_fma_f32 v[104:105], v[136:137], v[140:141], v[104:105]
	v_pk_fma_f32 v[154:155], v[136:137], v[144:145], v[154:155]
	v_pk_fma_f32 v[184:185], v[136:137], v[148:149], v[184:185]
	v_pk_fma_f32 v[212:213], v[136:137], v[152:153], v[212:213]
	ds_read_b128 v[134:137], v133 offset:32
	ds_read_b128 v[138:141], v156 offset:32
	ds_read_b128 v[142:145], v156 offset:288
	ds_read_b128 v[146:149], v156 offset:544
	ds_read_b128 v[150:153], v156 offset:800
	s_waitcnt lgkmcnt(5)
	v_pk_fma_f32 v[104:105], v[158:159], v[168:169], v[104:105]
	v_pk_fma_f32 v[154:155], v[158:159], v[172:173], v[154:155]
	v_pk_fma_f32 v[184:185], v[158:159], v[176:177], v[184:185]
	v_pk_fma_f32 v[212:213], v[158:159], v[180:181], v[212:213]
	v_pk_fma_f32 v[104:105], v[160:161], v[170:171], v[104:105]
	v_pk_fma_f32 v[154:155], v[160:161], v[174:175], v[154:155]
	v_pk_fma_f32 v[184:185], v[160:161], v[178:179], v[184:185]
	v_pk_fma_f32 v[212:213], v[160:161], v[182:183], v[212:213]
	ds_read_b128 v[158:161], v133 offset:48
	ds_read_b128 v[168:171], v156 offset:48
	ds_read_b128 v[172:175], v156 offset:304
	ds_read_b128 v[176:179], v156 offset:560
	ds_read_b128 v[180:183], v156 offset:816
	s_waitcnt lgkmcnt(5)
	v_pk_fma_f32 v[104:105], v[134:135], v[138:139], v[104:105]
	v_pk_fma_f32 v[154:155], v[134:135], v[142:143], v[154:155]
	v_pk_fma_f32 v[184:185], v[134:135], v[146:147], v[184:185]
	v_pk_fma_f32 v[212:213], v[134:135], v[150:151], v[212:213]
	v_pk_fma_f32 v[104:105], v[136:137], v[140:141], v[104:105]
	v_pk_fma_f32 v[154:155], v[136:137], v[144:145], v[154:155]
	v_pk_fma_f32 v[184:185], v[136:137], v[148:149], v[184:185]
	v_pk_fma_f32 v[212:213], v[136:137], v[152:153], v[212:213]
	s_waitcnt lgkmcnt(0)
	v_pk_fma_f32 v[104:105], v[158:159], v[168:169], v[104:105]
	v_pk_fma_f32 v[154:155], v[158:159], v[172:173], v[154:155]
	v_pk_fma_f32 v[184:185], v[158:159], v[176:177], v[184:185]
	v_pk_fma_f32 v[212:213], v[158:159], v[180:181], v[212:213]
	v_pk_fma_f32 v[104:105], v[160:161], v[170:171], v[104:105]
	v_pk_fma_f32 v[154:155], v[160:161], v[174:175], v[154:155]
	v_pk_fma_f32 v[184:185], v[160:161], v[178:179], v[184:185]
	v_pk_fma_f32 v[212:213], v[160:161], v[182:183], v[212:213]
	s_cbranch_scc1 .LBB0_859
	s_nop 0
	v_add_f32_e32 v100, v104, v105
	v_add_f32_e32 v101, v154, v155
	v_add_f32_e32 v102, v184, v185
	v_add_f32_e32 v103, v212, v213
	global_load_dword v104, v[46:47], off offset:3584
	s_waitcnt vmcnt(0)
	v_fmamk_f32 v100, v104, 0xbfb8aa3b, v100
	v_fmac_f32_e32 v101, 0xbfb8aa3b, v104
	v_fmamk_f32 v102, v104, 0xbfb8aa3b, v102
	v_fmac_f32_e32 v103, 0xbfb8aa3b, v104
	ds_write_b32 v115, v100 offset:7680
	ds_write_b32 v115, v101 offset:11904
	ds_write_b32 v115, v102 offset:16128
	ds_write_b32 v115, v103 offset:20352

; __global__ void __launch_bounds__(512, 2) mega_fwd(Params p) {
;     ...
;     for (int row = gw; row < MT; row += NGW) {
;         float rs = rstd_from(SSQ1, row);
;     ...
;         { const unsigned B = *(const unsigned*)(ws + WS_END), A4 = *(const unsigned*)(ws + WS_END + 4); const unsigned A = (A4 * 8u + 4095u) / 4096u; const unsigned F = 9u * A + B; if (row < MP) rs *= 1.0f + sqrtf(1.0f + (float)F); }
;     ...
; #pragma unroll
;         for (int j = 0; j < 4; ++j) { const int c = j * 256 + lane * 4; const f32x4 v = *(const f32x4*)(X + (size_t)row * 1024 + c), g = *(const f32x4*)(p.in[I_FG] + c);
;             __builtin_nontemporal_store(v * rs * g, (f32x4*)(p.out + (size_t)row * 1024 + c)); }
.LBB0_1750:
	s_nop 0
	v_lshl_add_u64 v[6:7], s[92:93], 0, v[2:3]
	s_add_u32 s3, s92, s4
	v_add_co_u32_e32 v30, vcc, s1, v6
	s_addc_u32 s10, s93, s5
	v_mov_b32_e32 v5, s3
	v_addc_co_u32_e32 v31, vcc, 0, v7, vcc
	v_add_co_u32_e32 v32, vcc, 0x269c8000, v5
	v_mov_b32_e32 v5, s10
	s_nop 0
	v_addc_co_u32_e32 v33, vcc, 0, v5, vcc
	flat_load_dwordx4 v[6:9], v[32:33]
	flat_load_dwordx4 v[10:13], v[32:33] offset:16
	flat_load_dwordx4 v[14:17], v[32:33] offset:32
	flat_load_dwordx4 v[18:21], v[32:33] offset:48
	flat_load_dwordx4 v[22:25], v[30:31]
	global_load_dwordx4 v[26:29], v[0:1], off
	flat_load_dwordx4 v[36:39], v[30:31] offset:1024
	flat_load_dwordx4 v[40:43], v[30:31] offset:2048
	flat_load_dwordx4 v[44:47], v[30:31] offset:3072
	global_load_dwordx4 v[48:51], v[0:1], off offset:1024
	global_load_dwordx4 v[52:55], v[0:1], off offset:2048
	global_load_dwordx4 v[56:59], v[0:1], off offset:3072
	v_lshl_add_u64 v[32:33], s[90:91], 0, v[2:3]
	s_add_i32 s0, s0, s2
	s_add_u32 s4, s4, s6
	s_addc_u32 s5, s5, s7
	v_lshl_add_u64 v[2:3], v[2:3], 0, s[8:9]
	s_cmpk_gt_i32 s0, 0x41ff
	s_waitcnt vmcnt(0) lgkmcnt(0)
	v_mov_b32_e32 v34, v7
	v_mov_b32_e32 v35, v8
	v_mov_b32_e32 v7, v9
	v_mov_b32_e32 v8, v11
	v_mov_b32_e32 v9, v12
	v_mov_b32_e32 v11, v13
	v_pk_add_f32 v[6:7], v[34:35], v[6:7]
	v_pk_add_f32 v[8:9], v[8:9], v[10:11]
	v_pk_add_f32 v[6:7], v[6:7], v[6:7] op_sel:[0,1] op_sel_hi:[1,0]
	v_pk_add_f32 v[8:9], v[8:9], v[8:9] op_sel:[0,1] op_sel_hi:[1,0]
	v_add_f32_e32 v12, v14, v15
	v_add_f32_e32 v14, v16, v17
	v_mov_b32_e32 v13, v20
	v_mov_b32_e32 v15, v21
	v_mov_b32_e32 v7, v18
	v_mov_b32_e32 v9, v19
	v_pk_add_f32 v[10:11], v[12:13], v[14:15]
	v_pk_add_f32 v[6:7], v[6:7], v[8:9]
	s_nop 0
	v_pk_add_f32 v[6:7], v[6:7], v[10:11]
	s_nop 0
	v_add_f32_e32 v5, v6, v7
	v_fmamk_f32 v5, v5, 0x3a800000, v4
	v_rsq_f32_e32 v14, v5
	s_nop 0
	v_pk_mul_f32 v[6:7], v[14:15], v[22:23] op_sel_hi:[0,1]
	v_pk_mul_f32 v[8:9], v[14:15], v[24:25] op_sel_hi:[0,1]
	v_pk_mul_f32 v[8:9], v[8:9], v[28:29]
	v_pk_mul_f32 v[6:7], v[6:7], v[26:27]
	global_store_dwordx4 v[32:33], v[6:9], off nt
	v_pk_mul_f32 v[62:63], v[14:15], v[38:39] op_sel_hi:[0,1]
	v_pk_mul_f32 v[60:61], v[14:15], v[36:37] op_sel_hi:[0,1]
	v_pk_mul_f32 v[60:61], v[60:61], v[48:49]
	v_pk_mul_f32 v[62:63], v[62:63], v[50:51]
	global_store_dwordx4 v[32:33], v[60:63], off offset:1024 nt
	v_pk_mul_f32 v[66:67], v[14:15], v[42:43] op_sel_hi:[0,1]
	v_pk_mul_f32 v[64:65], v[14:15], v[40:41] op_sel_hi:[0,1]
	v_pk_mul_f32 v[64:65], v[64:65], v[52:53]
	v_pk_mul_f32 v[66:67], v[66:67], v[54:55]
	global_store_dwordx4 v[32:33], v[64:67], off offset:2048 nt
	v_pk_mul_f32 v[70:71], v[14:15], v[46:47] op_sel_hi:[0,1]
	v_pk_mul_f32 v[68:69], v[14:15], v[44:45] op_sel_hi:[0,1]
	v_pk_mul_f32 v[68:69], v[68:69], v[56:57]
	v_pk_mul_f32 v[70:71], v[70:71], v[58:59]
	global_store_dwordx4 v[32:33], v[68:71], off offset:3072 nt
	s_cbranch_scc0 .LBB0_1750
